# wave_sum in gqa_prep, odd_prep and norm: 6-step ds_bpermute butterfly replaced by DPP row adds + readlane cross-row adds
# speedup vs baseline: 1.0457x; 1.0053x over previous
.LBB0_556:
	v_lshl_add_u64 v[22:23], s[80:81], 0, v[12:13]
	v_add_co_u32_e32 v22, vcc, 0x2448000, v22
	global_load_dwordx4 v[34:37], v[4:5], off
	s_nop 0
	v_addc_co_u32_e32 v23, vcc, 0, v23, vcc
	global_load_dwordx2 v[22:23], v[22:23], off offset:3072
	v_add_u32_e32 v21, s3, v24
	v_cmp_gt_i32_e64 s[44:45], s37, v21
	s_waitcnt vmcnt(0)
	v_and_b32_e32 v39, 0xffff0000, v23
	v_lshlrev_b32_e32 v38, 16, v23
	v_and_b32_e32 v23, 0xffff0000, v22
	v_lshlrev_b32_e32 v22, 16, v22
	v_pk_mul_f32 v[42:43], v[22:23], v[22:23]
	v_pk_mul_f32 v[40:41], v[38:39], v[38:39]
	v_add_f32_e32 v0, v42, v43
	v_add_f32_e32 v0, v0, v40
	v_add_f32_e32 v0, v0, v41
	s_waitcnt lgkmcnt(0)
	s_nop 1
	v_add_f32_dpp v19, v0, v0 quad_perm:[1,0,3,2] row_mask:0xf bank_mask:0xf
	s_nop 1
	v_add_f32_dpp v19, v19, v19 quad_perm:[2,3,0,1] row_mask:0xf bank_mask:0xf
	s_nop 1
	v_add_f32_dpp v19, v19, v19 row_ror:4 row_mask:0xf bank_mask:0xf
	s_nop 1
	v_add_f32_dpp v19, v19, v19 row_ror:8 row_mask:0xf bank_mask:0xf
	s_nop 1
	v_readlane_b32 s96, v19, 0
	v_readlane_b32 s97, v19, 16
	v_readlane_b32 s98, v19, 32
	v_readlane_b32 s99, v19, 48
	v_mov_b32_e32 v0, s96
	v_add_f32_e32 v0, s97, v0
	v_add_f32_e32 v0, s98, v0
	v_add_f32_e32 v0, s99, v0
	v_fmamk_f32 v0, v0, 0x3b800000, v203
	v_cmp_gt_f32_e32 vcc, s87, v0
	v_mul_f32_e32 v19, 0x4b800000, v0
	s_nop 0
	v_cndmask_b32_e32 v0, v0, v19, vcc
	v_rsq_f32_e32 v0, v0
	s_nop 0
	v_mul_f32_e32 v19, 0x45800000, v0
	v_cndmask_b32_e32 v0, v0, v19, vcc
	v_pk_mul_f32 v[22:23], v[0:1], v[22:23] op_sel_hi:[0,1]
	v_pk_mul_f32 v[22:23], v[34:35], v[22:23]
	v_pk_mul_f32 v[34:35], v[0:1], v[38:39] op_sel_hi:[0,1]
	v_pk_mul_f32 v[34:35], v[36:37], v[34:35]
	v_cvt_pk_bf16_f32 v22, v22, v23
	v_cvt_pk_bf16_f32 v23, v34, v35
	v_lshl_add_u64 v[34:35], s[80:81], 0, v[10:11]
	global_store_dwordx2 v[34:35], v[22:23], off
	v_lshl_add_u64 v[22:23], s[80:81], 0, v[16:17]
	global_load_dword v0, v[22:23], off
	s_waitcnt vmcnt(0)
	v_and_b32_e32 v23, 0xffff0000, v0
	v_lshlrev_b32_e32 v22, 16, v0
	v_pk_mul_f32 v[34:35], v[22:23], v[22:23]
	s_nop 0
	v_add_f32_e32 v0, v34, v35
	global_load_dwordx2 v[34:35], v[6:7], off
	s_waitcnt lgkmcnt(0)
	s_nop 1
	v_add_f32_dpp v19, v0, v0 quad_perm:[1,0,3,2] row_mask:0xf bank_mask:0xf
	s_nop 1
	v_add_f32_dpp v19, v19, v19 quad_perm:[2,3,0,1] row_mask:0xf bank_mask:0xf
	s_nop 1
	v_add_f32_dpp v19, v19, v19 row_ror:4 row_mask:0xf bank_mask:0xf
	s_nop 1
	v_add_f32_dpp v19, v19, v19 row_ror:8 row_mask:0xf bank_mask:0xf
	s_nop 1
	v_readlane_b32 s96, v19, 0
	v_readlane_b32 s97, v19, 16
	v_readlane_b32 s98, v19, 32
	v_readlane_b32 s99, v19, 48
	v_mov_b32_e32 v0, s96
	v_add_f32_e32 v0, s97, v0
	v_add_f32_e32 v0, s98, v0
	v_add_f32_e32 v0, s99, v0
	v_fmamk_f32 v0, v0, 0x3c000000, v203
	v_cmp_gt_f32_e32 vcc, s87, v0
	v_mul_f32_e32 v19, 0x4b800000, v0
	s_nop 0
	v_cndmask_b32_e32 v0, v0, v19, vcc
	v_rsq_f32_e32 v0, v0
	s_nop 0
	v_mul_f32_e32 v19, 0x45800000, v0
	v_cndmask_b32_e32 v0, v0, v19, vcc
	v_pk_mul_f32 v[22:23], v[0:1], v[22:23] op_sel_hi:[0,1]
	v_cmp_lt_i32_e32 vcc, s91, v21
	s_waitcnt vmcnt(0)
	v_pk_mul_f32 v[22:23], v[34:35], v[22:23]
	s_nop 0
	v_cvt_pk_bf16_f32 v0, v22, v23
	v_lshl_add_u64 v[34:35], s[80:81], 0, v[8:9]
	global_store_dword v[34:35], v0, off
	v_ashrrev_i32_e32 v0, 7, v21
	v_and_b32_e32 v34, -2, v0
	s_and_saveexec_b64 s[14:15], s[44:45]
	s_cbranch_execz .LBB0_558
	v_add_u32_e32 v36, s58, v34
	v_ashrrev_i32_e32 v37, 31, v36
	v_and_b32_e32 v0, 0x7f80, v33
	v_lshlrev_b64 v[36:37], 17, v[36:37]
	v_lshl_add_u64 v[36:37], s[50:51], 0, v[36:37]
	v_lshlrev_b32_e32 v0, 2, v0
	v_lshl_add_u64 v[36:37], v[36:37], 0, v[0:1]
	v_mov_b32_e32 v19, v1
	v_lshl_add_u64 v[36:37], v[36:37], 0, v[18:19]
	global_store_dwordx2 v[36:37], v[22:23], off

.LBB0_682:
	v_add_u32_e32 v37, s3, v45
	v_add_u32_e32 v10, 1, v37
	v_mul_hi_i32 v11, v10, s33
	v_lshrrev_b32_e32 v12, 31, v11
	v_add_u32_e32 v71, v11, v12
	v_add_u32_e32 v12, 2, v37
	v_mul_hi_i32 v13, v12, s33
	v_lshrrev_b32_e32 v14, 31, v13
	v_add_u32_e32 v68, v13, v14
	v_add_u32_e32 v14, 3, v37
	v_mul_hi_i32 v0, v37, s33
	v_mul_hi_i32 v15, v14, s33
	v_lshrrev_b32_e32 v8, 31, v0
	v_lshrrev_b32_e32 v16, 31, v15
	v_add_u32_e32 v42, v0, v8
	v_mul_lo_u32 v11, v71, 6
	v_add_u32_e32 v65, v15, v16
	v_mul_lo_u32 v0, v42, 6
	v_sub_u32_e32 v29, v10, v11
	v_mul_lo_u32 v13, v68, 6
	v_mul_lo_u32 v15, v65, 6
	v_sub_u32_e32 v33, v37, v0
	v_mov_b64_e32 v[40:41], s[74:75]
	v_add_u32_e32 v32, s24, v71
	v_lshlrev_b32_e32 v34, 7, v29
	v_sub_u32_e32 v25, v12, v13
	v_sub_u32_e32 v21, v14, v15
	v_add_u32_e32 v36, s24, v42
	v_lshlrev_b32_e32 v38, 7, v33
	v_mad_i64_i32 v[10:11], s[6:7], v32, s88, v[40:41]
	v_ashrrev_i32_e32 v35, 31, v34
	v_add_u32_e32 v28, s24, v68
	v_lshlrev_b32_e32 v30, 7, v25
	v_add_u32_e32 v24, s24, v65
	v_lshlrev_b32_e32 v26, 7, v21
	v_mad_i64_i32 v[8:9], s[6:7], v36, s88, v[40:41]
	v_ashrrev_i32_e32 v39, 31, v38
	v_lshlrev_b32_e32 v0, 1, v2
	v_lshl_add_u64 v[10:11], v[34:35], 1, v[10:11]
	v_mad_i64_i32 v[12:13], s[6:7], v28, s88, v[40:41]
	v_ashrrev_i32_e32 v31, 31, v30
	v_mad_i64_i32 v[14:15], s[6:7], v24, s88, v[40:41]
	v_ashrrev_i32_e32 v27, 31, v26
	v_lshl_add_u64 v[8:9], v[38:39], 1, v[8:9]
	v_lshl_add_u64 v[10:11], v[10:11], 0, v[0:1]
	v_lshl_add_u64 v[12:13], v[30:31], 1, v[12:13]
	v_lshl_add_u64 v[14:15], v[26:27], 1, v[14:15]
	v_lshl_add_u64 v[8:9], v[8:9], 0, v[0:1]
	v_lshl_add_u64 v[12:13], v[12:13], 0, v[0:1]
	v_lshl_add_u64 v[14:15], v[14:15], 0, v[0:1]
	global_load_ushort v72, v[10:11], off offset:3072
	global_load_ushort v73, v[10:11], off offset:3200
	global_load_ushort v69, v[12:13], off offset:3072
	global_load_ushort v70, v[12:13], off offset:3200
	global_load_ushort v66, v[14:15], off offset:3072
	global_load_ushort v67, v[14:15], off offset:3200
	global_load_ushort v43, v[8:9], off offset:3072
	global_load_ushort v78, v[8:9], off offset:3200
	v_add_u32_e32 v16, 4, v37
	v_mul_hi_i32 v17, v16, s33
	v_lshrrev_b32_e32 v18, 31, v17
	v_add_u32_e32 v17, v17, v18
	v_mul_lo_u32 v8, v17, 6
	v_sub_u32_e32 v62, v16, v8
	v_add_u32_e32 v20, s24, v17
	v_lshlrev_b32_e32 v22, 7, v62
	v_mad_i64_i32 v[8:9], s[6:7], v20, s88, v[40:41]
	v_ashrrev_i32_e32 v23, 31, v22
	v_lshl_add_u64 v[8:9], v[22:23], 1, v[8:9]
	v_lshl_add_u64 v[54:55], v[8:9], 0, v[0:1]
	v_add_u32_e32 v8, 5, v37
	v_mul_hi_i32 v9, v8, s33
	v_lshrrev_b32_e32 v10, 31, v9
	v_add_u32_e32 v59, v9, v10
	v_mul_lo_u32 v9, v59, 6
	v_sub_u32_e32 v13, v8, v9
	v_add_u32_e32 v16, s24, v59
	v_lshlrev_b32_e32 v18, 7, v13
	v_mad_i64_i32 v[8:9], s[6:7], v16, s88, v[40:41]
	v_ashrrev_i32_e32 v19, 31, v18
	v_lshl_add_u64 v[8:9], v[18:19], 1, v[8:9]
	v_lshl_add_u64 v[74:75], v[8:9], 0, v[0:1]
	v_add_u32_e32 v8, 6, v37
	v_mul_hi_i32 v9, v8, s33
	v_lshrrev_b32_e32 v10, 31, v9
	v_add_u32_e32 v56, v9, v10
	v_mul_lo_u32 v9, v56, 6
	v_sub_u32_e32 v9, v8, v9
	v_add_u32_e32 v12, s24, v56
	v_lshlrev_b32_e32 v14, 7, v9
	v_mad_i64_i32 v[10:11], s[6:7], v12, s88, v[40:41]
	v_ashrrev_i32_e32 v15, 31, v14
	v_lshl_add_u64 v[10:11], v[14:15], 1, v[10:11]
	v_lshl_add_u64 v[76:77], v[10:11], 0, v[0:1]
	v_add_u32_e32 v10, 7, v37
	v_mul_hi_i32 v8, v10, s33
	v_lshrrev_b32_e32 v11, 31, v8
	v_add_u32_e32 v53, v8, v11
	v_mul_lo_u32 v11, v53, 6
	v_sub_u32_e32 v52, v10, v11
	v_add_u32_e32 v8, s24, v53
	v_lshlrev_b32_e32 v10, 7, v52
	v_mad_i64_i32 v[40:41], s[6:7], v8, s88, v[40:41]
	v_ashrrev_i32_e32 v11, 31, v10
	v_lshl_add_u64 v[40:41], v[10:11], 1, v[40:41]
	v_lshl_add_u64 v[40:41], v[40:41], 0, v[0:1]
	global_load_ushort v63, v[54:55], off offset:3072
	global_load_ushort v64, v[54:55], off offset:3200
	global_load_ushort v60, v[74:75], off offset:3072
	global_load_ushort v61, v[74:75], off offset:3200
	global_load_ushort v57, v[76:77], off offset:3072
	global_load_ushort v58, v[76:77], off offset:3200
	s_nop 0
	global_load_ushort v54, v[40:41], off offset:3072
	global_load_ushort v55, v[40:41], off offset:3200
	v_cmp_lt_i32_e64 s[42:43], 3, v33
	s_waitcnt vmcnt(9)
	v_lshlrev_b32_e32 v40, 16, v43
	s_waitcnt vmcnt(8)
	v_lshlrev_b32_e32 v41, 16, v78
	v_pk_mul_f32 v[74:75], v[40:41], v[40:41]
	s_nop 0
	v_add_f32_e32 v37, v74, v75
	s_waitcnt lgkmcnt(0)
	s_nop 1
	v_add_f32_dpp v43, v37, v37 quad_perm:[1,0,3,2] row_mask:0xf bank_mask:0xf
	s_nop 1
	v_add_f32_dpp v43, v43, v43 quad_perm:[2,3,0,1] row_mask:0xf bank_mask:0xf
	s_nop 1
	v_add_f32_dpp v43, v43, v43 row_ror:4 row_mask:0xf bank_mask:0xf
	s_nop 1
	v_add_f32_dpp v43, v43, v43 row_ror:8 row_mask:0xf bank_mask:0xf
	s_nop 1
	v_readlane_b32 s96, v43, 0
	v_readlane_b32 s97, v43, 16
	v_readlane_b32 s98, v43, 32
	v_readlane_b32 s99, v43, 48
	v_mov_b32_e32 v37, s96
	v_add_f32_e32 v37, s97, v37
	v_add_f32_e32 v37, s98, v37
	v_add_f32_e32 v37, s99, v37
	v_fmamk_f32 v37, v37, 0x3c000000, v203
	v_mul_f32_e32 v43, 0x4b800000, v37
	v_cmp_gt_f32_e32 vcc, s87, v37
	s_nop 1
	v_cndmask_b32_e32 v37, v37, v43, vcc
	v_rsq_f32_e32 v43, v37
	v_ashrrev_i32_e32 v37, 31, v36
	v_mul_f32_e32 v74, 0x45800000, v43
	v_cndmask_b32_e32 v74, v43, v74, vcc
	v_cmp_gt_i32_e32 vcc, 4, v33
	v_pk_mul_f32 v[40:41], v[74:75], v[40:41] op_sel_hi:[0,1]
	s_nop 0
	v_cndmask_b32_e32 v75, v5, v3, vcc
	v_cndmask_b32_e32 v74, v6, v4, vcc
	v_pk_mul_f32 v[40:41], v[74:75], v[40:41]
	v_cmp_lt_i32_e32 vcc, s91, v36
	s_and_saveexec_b64 s[6:7], vcc
	s_xor_b64 s[14:15], exec, s[6:7]
	s_cbranch_execz .LBB0_686
	v_bfe_u32 v33, v36, 6, 4
	v_and_b32_e32 v42, 63, v42
	v_cndmask_b32_e64 v33, v42, v33, s[40:41]
	v_cvt_f32_ubyte0_e32 v33, v33
	v_mul_f32_e32 v33, v7, v33
	v_mul_f32_e32 v33, 0.15915494, v33
	v_sin_f32_e32 v42, v33
	v_cos_f32_e32 v74, v33
	v_pk_mul_f32 v[42:43], v[42:43], v[40:41] op_sel:[0,1] op_sel_hi:[0,0]
	v_pk_mul_f32 v[76:77], v[74:75], v[40:41] op_sel_hi:[0,1]
	v_pk_fma_f32 v[40:41], v[74:75], v[40:41], v[42:43] op_sel_hi:[0,1,1]
	v_sub_f32_e32 v40, v76, v42
	s_andn2_saveexec_b64 s[20:21], s[14:15]
	s_cbranch_execnz .LBB0_687

.LBB0_692:
	s_or_b64 exec, exec, s[14:15]
	v_bfe_u32 v36, v40, 16, 1
	v_add3_u32 v38, v40, v36, s27
	v_lshl_add_u64 v[36:37], v[42:43], 0, v[0:1]
	global_store_short_d16_hi v[36:37], v38, off
	v_bfe_u32 v38, v41, 16, 1
	v_add3_u32 v38, v41, v38, s27
	global_store_short_d16_hi v[36:37], v38, off offset:128
	v_lshlrev_b32_e32 v37, 16, v73
	v_lshlrev_b32_e32 v36, 16, v72
	v_pk_mul_f32 v[38:39], v[36:37], v[36:37]
	v_cmp_gt_i32_e32 vcc, 4, v29
	v_add_f32_e32 v38, v38, v39
	v_ashrrev_i32_e32 v33, 31, v32
	v_cmp_lt_i32_e64 s[42:43], 3, v29
	s_waitcnt lgkmcnt(0)
	s_nop 1
	v_add_f32_dpp v39, v38, v38 quad_perm:[1,0,3,2] row_mask:0xf bank_mask:0xf
	s_nop 1
	v_add_f32_dpp v39, v39, v39 quad_perm:[2,3,0,1] row_mask:0xf bank_mask:0xf
	s_nop 1
	v_add_f32_dpp v39, v39, v39 row_ror:4 row_mask:0xf bank_mask:0xf
	s_nop 1
	v_add_f32_dpp v39, v39, v39 row_ror:8 row_mask:0xf bank_mask:0xf
	s_nop 1
	v_readlane_b32 s96, v39, 0
	v_readlane_b32 s97, v39, 16
	v_readlane_b32 s98, v39, 32
	v_readlane_b32 s99, v39, 48
	v_mov_b32_e32 v38, s96
	v_add_f32_e32 v38, s97, v38
	v_add_f32_e32 v38, s98, v38
	v_add_f32_e32 v38, s99, v38
	v_fmamk_f32 v38, v38, 0x3c000000, v203
	v_cmp_gt_f32_e64 s[44:45], s87, v38
	v_mul_f32_e32 v39, 0x4b800000, v38
	s_nop 0
	v_cndmask_b32_e64 v38, v38, v39, s[44:45]
	v_rsq_f32_e32 v38, v38
	s_nop 0
	v_mul_f32_e32 v39, 0x45800000, v38
	v_cndmask_b32_e64 v38, v38, v39, s[44:45]
	v_pk_mul_f32 v[36:37], v[38:39], v[36:37] op_sel_hi:[0,1]
	v_cndmask_b32_e32 v39, v5, v3, vcc
	v_cndmask_b32_e32 v38, v6, v4, vcc
	v_pk_mul_f32 v[36:37], v[38:39], v[36:37]
	v_cmp_lt_i32_e32 vcc, s91, v32
	s_and_saveexec_b64 s[6:7], vcc
	s_xor_b64 s[14:15], exec, s[6:7]
	s_cbranch_execz .LBB0_696
	v_bfe_u32 v29, v32, 6, 4
	v_and_b32_e32 v38, 63, v71
	v_cndmask_b32_e64 v29, v38, v29, s[40:41]
	v_cvt_f32_ubyte0_e32 v29, v29
	v_mul_f32_e32 v29, v7, v29
	v_mul_f32_e32 v29, 0.15915494, v29
	v_sin_f32_e32 v38, v29
	v_cos_f32_e32 v40, v29
	v_pk_mul_f32 v[38:39], v[38:39], v[36:37] op_sel:[0,1] op_sel_hi:[0,0]
	v_pk_mul_f32 v[42:43], v[40:41], v[36:37] op_sel_hi:[0,1]
	v_pk_fma_f32 v[36:37], v[40:41], v[36:37], v[38:39] op_sel_hi:[0,1,1]
	v_sub_f32_e32 v36, v42, v38
	s_andn2_saveexec_b64 s[20:21], s[14:15]
	s_cbranch_execnz .LBB0_697

.LBB0_702:
	s_or_b64 exec, exec, s[14:15]
	v_bfe_u32 v32, v36, 16, 1
	v_add3_u32 v34, v36, v32, s27
	v_lshl_add_u64 v[32:33], v[38:39], 0, v[0:1]
	global_store_short_d16_hi v[32:33], v34, off
	v_bfe_u32 v34, v37, 16, 1
	v_add3_u32 v34, v37, v34, s27
	global_store_short_d16_hi v[32:33], v34, off offset:128
	v_lshlrev_b32_e32 v33, 16, v70
	v_lshlrev_b32_e32 v32, 16, v69
	v_pk_mul_f32 v[34:35], v[32:33], v[32:33]
	v_cmp_gt_i32_e32 vcc, 4, v25
	v_add_f32_e32 v34, v34, v35
	v_ashrrev_i32_e32 v29, 31, v28
	v_cmp_lt_i32_e64 s[42:43], 3, v25
	s_waitcnt lgkmcnt(0)
	s_nop 1
	v_add_f32_dpp v35, v34, v34 quad_perm:[1,0,3,2] row_mask:0xf bank_mask:0xf
	s_nop 1
	v_add_f32_dpp v35, v35, v35 quad_perm:[2,3,0,1] row_mask:0xf bank_mask:0xf
	s_nop 1
	v_add_f32_dpp v35, v35, v35 row_ror:4 row_mask:0xf bank_mask:0xf
	s_nop 1
	v_add_f32_dpp v35, v35, v35 row_ror:8 row_mask:0xf bank_mask:0xf
	s_nop 1
	v_readlane_b32 s96, v35, 0
	v_readlane_b32 s97, v35, 16
	v_readlane_b32 s98, v35, 32
	v_readlane_b32 s99, v35, 48
	v_mov_b32_e32 v34, s96
	v_add_f32_e32 v34, s97, v34
	v_add_f32_e32 v34, s98, v34
	v_add_f32_e32 v34, s99, v34
	v_fmamk_f32 v34, v34, 0x3c000000, v203
	v_cmp_gt_f32_e64 s[44:45], s87, v34
	v_mul_f32_e32 v35, 0x4b800000, v34
	s_nop 0
	v_cndmask_b32_e64 v34, v34, v35, s[44:45]
	v_rsq_f32_e32 v34, v34
	s_nop 0
	v_mul_f32_e32 v35, 0x45800000, v34
	v_cndmask_b32_e64 v34, v34, v35, s[44:45]
	v_pk_mul_f32 v[32:33], v[34:35], v[32:33] op_sel_hi:[0,1]
	v_cndmask_b32_e32 v35, v5, v3, vcc
	v_cndmask_b32_e32 v34, v6, v4, vcc
	v_pk_mul_f32 v[32:33], v[34:35], v[32:33]
	v_cmp_lt_i32_e32 vcc, s91, v28
	s_and_saveexec_b64 s[6:7], vcc
	s_xor_b64 s[14:15], exec, s[6:7]
	s_cbranch_execz .LBB0_706
	v_bfe_u32 v25, v28, 6, 4
	v_and_b32_e32 v34, 63, v68
	v_cndmask_b32_e64 v25, v34, v25, s[40:41]
	v_cvt_f32_ubyte0_e32 v25, v25
	v_mul_f32_e32 v25, v7, v25
	v_mul_f32_e32 v25, 0.15915494, v25
	v_sin_f32_e32 v34, v25
	v_cos_f32_e32 v36, v25
	v_pk_mul_f32 v[34:35], v[34:35], v[32:33] op_sel:[0,1] op_sel_hi:[0,0]
	v_pk_mul_f32 v[38:39], v[36:37], v[32:33] op_sel_hi:[0,1]
	v_pk_fma_f32 v[32:33], v[36:37], v[32:33], v[34:35] op_sel_hi:[0,1,1]
	v_sub_f32_e32 v32, v38, v34
	s_andn2_saveexec_b64 s[20:21], s[14:15]
	s_cbranch_execnz .LBB0_707

.LBB0_712:
	s_or_b64 exec, exec, s[14:15]
	v_bfe_u32 v28, v32, 16, 1
	v_add3_u32 v30, v32, v28, s27
	v_lshl_add_u64 v[28:29], v[34:35], 0, v[0:1]
	global_store_short_d16_hi v[28:29], v30, off
	v_bfe_u32 v30, v33, 16, 1
	v_add3_u32 v30, v33, v30, s27
	global_store_short_d16_hi v[28:29], v30, off offset:128
	v_lshlrev_b32_e32 v29, 16, v67
	v_lshlrev_b32_e32 v28, 16, v66
	v_pk_mul_f32 v[30:31], v[28:29], v[28:29]
	v_cmp_gt_i32_e32 vcc, 4, v21
	v_add_f32_e32 v30, v30, v31
	v_ashrrev_i32_e32 v25, 31, v24
	v_cmp_lt_i32_e64 s[42:43], 3, v21
	s_waitcnt lgkmcnt(0)
	s_nop 1
	v_add_f32_dpp v31, v30, v30 quad_perm:[1,0,3,2] row_mask:0xf bank_mask:0xf
	s_nop 1
	v_add_f32_dpp v31, v31, v31 quad_perm:[2,3,0,1] row_mask:0xf bank_mask:0xf
	s_nop 1
	v_add_f32_dpp v31, v31, v31 row_ror:4 row_mask:0xf bank_mask:0xf
	s_nop 1
	v_add_f32_dpp v31, v31, v31 row_ror:8 row_mask:0xf bank_mask:0xf
	s_nop 1
	v_readlane_b32 s96, v31, 0
	v_readlane_b32 s97, v31, 16
	v_readlane_b32 s98, v31, 32
	v_readlane_b32 s99, v31, 48
	v_mov_b32_e32 v30, s96
	v_add_f32_e32 v30, s97, v30
	v_add_f32_e32 v30, s98, v30
	v_add_f32_e32 v30, s99, v30
	v_fmamk_f32 v30, v30, 0x3c000000, v203
	v_cmp_gt_f32_e64 s[44:45], s87, v30
	v_mul_f32_e32 v31, 0x4b800000, v30
	s_nop 0
	v_cndmask_b32_e64 v30, v30, v31, s[44:45]
	v_rsq_f32_e32 v30, v30
	s_nop 0
	v_mul_f32_e32 v31, 0x45800000, v30
	v_cndmask_b32_e64 v30, v30, v31, s[44:45]
	v_pk_mul_f32 v[28:29], v[30:31], v[28:29] op_sel_hi:[0,1]
	v_cndmask_b32_e32 v31, v5, v3, vcc
	v_cndmask_b32_e32 v30, v6, v4, vcc
	v_pk_mul_f32 v[28:29], v[30:31], v[28:29]
	v_cmp_lt_i32_e32 vcc, s91, v24
	s_and_saveexec_b64 s[6:7], vcc
	s_xor_b64 s[14:15], exec, s[6:7]
	s_cbranch_execz .LBB0_716
	v_bfe_u32 v21, v24, 6, 4
	v_and_b32_e32 v30, 63, v65
	v_cndmask_b32_e64 v21, v30, v21, s[40:41]
	v_cvt_f32_ubyte0_e32 v21, v21
	v_mul_f32_e32 v21, v7, v21
	v_mul_f32_e32 v21, 0.15915494, v21
	v_sin_f32_e32 v30, v21
	v_cos_f32_e32 v32, v21
	v_pk_mul_f32 v[30:31], v[30:31], v[28:29] op_sel:[0,1] op_sel_hi:[0,0]
	v_pk_mul_f32 v[34:35], v[32:33], v[28:29] op_sel_hi:[0,1]
	v_pk_fma_f32 v[28:29], v[32:33], v[28:29], v[30:31] op_sel_hi:[0,1,1]
	v_sub_f32_e32 v28, v34, v30
	s_andn2_saveexec_b64 s[20:21], s[14:15]
	s_cbranch_execnz .LBB0_717

.LBB0_722:
	s_or_b64 exec, exec, s[14:15]
	v_bfe_u32 v24, v28, 16, 1
	v_add3_u32 v26, v28, v24, s27
	v_lshl_add_u64 v[24:25], v[30:31], 0, v[0:1]
	global_store_short_d16_hi v[24:25], v26, off
	v_bfe_u32 v26, v29, 16, 1
	v_add3_u32 v26, v29, v26, s27
	global_store_short_d16_hi v[24:25], v26, off offset:128
	s_waitcnt vmcnt(14)
	v_lshlrev_b32_e32 v25, 16, v64
	v_lshlrev_b32_e32 v24, 16, v63
	v_pk_mul_f32 v[26:27], v[24:25], v[24:25]
	v_cmp_gt_i32_e32 vcc, 4, v62
	v_add_f32_e32 v26, v26, v27
	v_ashrrev_i32_e32 v21, 31, v20
	v_cmp_lt_i32_e64 s[42:43], 3, v62
	s_waitcnt lgkmcnt(0)
	s_nop 1
	v_add_f32_dpp v27, v26, v26 quad_perm:[1,0,3,2] row_mask:0xf bank_mask:0xf
	s_nop 1
	v_add_f32_dpp v27, v27, v27 quad_perm:[2,3,0,1] row_mask:0xf bank_mask:0xf
	s_nop 1
	v_add_f32_dpp v27, v27, v27 row_ror:4 row_mask:0xf bank_mask:0xf
	s_nop 1
	v_add_f32_dpp v27, v27, v27 row_ror:8 row_mask:0xf bank_mask:0xf
	s_nop 1
	v_readlane_b32 s96, v27, 0
	v_readlane_b32 s97, v27, 16
	v_readlane_b32 s98, v27, 32
	v_readlane_b32 s99, v27, 48
	v_mov_b32_e32 v26, s96
	v_add_f32_e32 v26, s97, v26
	v_add_f32_e32 v26, s98, v26
	v_add_f32_e32 v26, s99, v26
	v_fmamk_f32 v26, v26, 0x3c000000, v203
	v_cmp_gt_f32_e64 s[44:45], s87, v26
	v_mul_f32_e32 v27, 0x4b800000, v26
	s_nop 0
	v_cndmask_b32_e64 v26, v26, v27, s[44:45]
	v_rsq_f32_e32 v26, v26
	s_nop 0
	v_mul_f32_e32 v27, 0x45800000, v26
	v_cndmask_b32_e64 v26, v26, v27, s[44:45]
	v_pk_mul_f32 v[24:25], v[26:27], v[24:25] op_sel_hi:[0,1]
	v_cndmask_b32_e32 v27, v5, v3, vcc
	v_cndmask_b32_e32 v26, v6, v4, vcc
	v_pk_mul_f32 v[24:25], v[26:27], v[24:25]
	v_cmp_lt_i32_e32 vcc, s91, v20
	s_and_saveexec_b64 s[6:7], vcc
	s_xor_b64 s[14:15], exec, s[6:7]
	s_cbranch_execz .LBB0_726
	v_bfe_u32 v26, v20, 6, 4
	v_and_b32_e32 v17, 63, v17
	v_cndmask_b32_e64 v17, v17, v26, s[40:41]
	v_cvt_f32_ubyte0_e32 v17, v17
	v_mul_f32_e32 v17, v7, v17
	v_mul_f32_e32 v17, 0.15915494, v17
	v_sin_f32_e32 v26, v17
	v_cos_f32_e32 v28, v17
	v_pk_mul_f32 v[26:27], v[26:27], v[24:25] op_sel:[0,1] op_sel_hi:[0,0]
	v_pk_mul_f32 v[30:31], v[28:29], v[24:25] op_sel_hi:[0,1]
	v_pk_fma_f32 v[24:25], v[28:29], v[24:25], v[26:27] op_sel_hi:[0,1,1]
	v_sub_f32_e32 v24, v30, v26
	s_andn2_saveexec_b64 s[20:21], s[14:15]
	s_cbranch_execnz .LBB0_727

.LBB0_732:
	s_or_b64 exec, exec, s[14:15]
	v_bfe_u32 v20, v24, 16, 1
	v_add3_u32 v22, v24, v20, s27
	v_lshl_add_u64 v[20:21], v[26:27], 0, v[0:1]
	global_store_short_d16_hi v[20:21], v22, off
	v_bfe_u32 v22, v25, 16, 1
	v_add3_u32 v22, v25, v22, s27
	global_store_short_d16_hi v[20:21], v22, off offset:128
	s_waitcnt vmcnt(14)
	v_lshlrev_b32_e32 v21, 16, v61
	v_lshlrev_b32_e32 v20, 16, v60
	v_pk_mul_f32 v[22:23], v[20:21], v[20:21]
	v_cmp_gt_i32_e32 vcc, 4, v13
	v_add_f32_e32 v22, v22, v23
	v_ashrrev_i32_e32 v17, 31, v16
	v_cmp_lt_i32_e64 s[42:43], 3, v13
	s_waitcnt lgkmcnt(0)
	s_nop 1
	v_add_f32_dpp v23, v22, v22 quad_perm:[1,0,3,2] row_mask:0xf bank_mask:0xf
	s_nop 1
	v_add_f32_dpp v23, v23, v23 quad_perm:[2,3,0,1] row_mask:0xf bank_mask:0xf
	s_nop 1
	v_add_f32_dpp v23, v23, v23 row_ror:4 row_mask:0xf bank_mask:0xf
	s_nop 1
	v_add_f32_dpp v23, v23, v23 row_ror:8 row_mask:0xf bank_mask:0xf
	s_nop 1
	v_readlane_b32 s96, v23, 0
	v_readlane_b32 s97, v23, 16
	v_readlane_b32 s98, v23, 32
	v_readlane_b32 s99, v23, 48
	v_mov_b32_e32 v22, s96
	v_add_f32_e32 v22, s97, v22
	v_add_f32_e32 v22, s98, v22
	v_add_f32_e32 v22, s99, v22
	v_fmamk_f32 v22, v22, 0x3c000000, v203
	v_cmp_gt_f32_e64 s[44:45], s87, v22
	v_mul_f32_e32 v23, 0x4b800000, v22
	s_nop 0
	v_cndmask_b32_e64 v22, v22, v23, s[44:45]
	v_rsq_f32_e32 v22, v22
	s_nop 0
	v_mul_f32_e32 v23, 0x45800000, v22
	v_cndmask_b32_e64 v22, v22, v23, s[44:45]
	v_pk_mul_f32 v[20:21], v[22:23], v[20:21] op_sel_hi:[0,1]
	v_cndmask_b32_e32 v23, v5, v3, vcc
	v_cndmask_b32_e32 v22, v6, v4, vcc
	v_pk_mul_f32 v[20:21], v[22:23], v[20:21]
	v_cmp_lt_i32_e32 vcc, s91, v16
	s_and_saveexec_b64 s[6:7], vcc
	s_xor_b64 s[14:15], exec, s[6:7]
	s_cbranch_execz .LBB0_736
	v_bfe_u32 v13, v16, 6, 4
	v_and_b32_e32 v22, 63, v59
	v_cndmask_b32_e64 v13, v22, v13, s[40:41]
	v_cvt_f32_ubyte0_e32 v13, v13
	v_mul_f32_e32 v13, v7, v13
	v_mul_f32_e32 v13, 0.15915494, v13
	v_sin_f32_e32 v22, v13
	v_cos_f32_e32 v24, v13
	v_pk_mul_f32 v[22:23], v[22:23], v[20:21] op_sel:[0,1] op_sel_hi:[0,0]
	v_pk_mul_f32 v[26:27], v[24:25], v[20:21] op_sel_hi:[0,1]
	v_pk_fma_f32 v[20:21], v[24:25], v[20:21], v[22:23] op_sel_hi:[0,1,1]
	v_sub_f32_e32 v20, v26, v22
	s_andn2_saveexec_b64 s[20:21], s[14:15]
	s_cbranch_execnz .LBB0_737

.LBB0_742:
	s_or_b64 exec, exec, s[14:15]
	v_bfe_u32 v16, v20, 16, 1
	v_add3_u32 v18, v20, v16, s27
	v_lshl_add_u64 v[16:17], v[22:23], 0, v[0:1]
	global_store_short_d16_hi v[16:17], v18, off
	v_bfe_u32 v18, v21, 16, 1
	v_add3_u32 v18, v21, v18, s27
	global_store_short_d16_hi v[16:17], v18, off offset:128
	s_waitcnt vmcnt(14)
	v_lshlrev_b32_e32 v17, 16, v58
	v_lshlrev_b32_e32 v16, 16, v57
	v_pk_mul_f32 v[18:19], v[16:17], v[16:17]
	v_cmp_gt_i32_e32 vcc, 4, v9
	v_add_f32_e32 v18, v18, v19
	v_ashrrev_i32_e32 v13, 31, v12
	v_cmp_lt_i32_e64 s[42:43], 3, v9
	s_waitcnt lgkmcnt(0)
	s_nop 1
	v_add_f32_dpp v19, v18, v18 quad_perm:[1,0,3,2] row_mask:0xf bank_mask:0xf
	s_nop 1
	v_add_f32_dpp v19, v19, v19 quad_perm:[2,3,0,1] row_mask:0xf bank_mask:0xf
	s_nop 1
	v_add_f32_dpp v19, v19, v19 row_ror:4 row_mask:0xf bank_mask:0xf
	s_nop 1
	v_add_f32_dpp v19, v19, v19 row_ror:8 row_mask:0xf bank_mask:0xf
	s_nop 1
	v_readlane_b32 s96, v19, 0
	v_readlane_b32 s97, v19, 16
	v_readlane_b32 s98, v19, 32
	v_readlane_b32 s99, v19, 48
	v_mov_b32_e32 v18, s96
	v_add_f32_e32 v18, s97, v18
	v_add_f32_e32 v18, s98, v18
	v_add_f32_e32 v18, s99, v18
	v_fmamk_f32 v18, v18, 0x3c000000, v203
	v_cmp_gt_f32_e64 s[44:45], s87, v18
	v_mul_f32_e32 v19, 0x4b800000, v18
	s_nop 0
	v_cndmask_b32_e64 v18, v18, v19, s[44:45]
	v_rsq_f32_e32 v18, v18
	s_nop 0
	v_mul_f32_e32 v19, 0x45800000, v18
	v_cndmask_b32_e64 v18, v18, v19, s[44:45]
	v_pk_mul_f32 v[16:17], v[18:19], v[16:17] op_sel_hi:[0,1]
	v_cndmask_b32_e32 v19, v5, v3, vcc
	v_cndmask_b32_e32 v18, v6, v4, vcc
	v_pk_mul_f32 v[16:17], v[18:19], v[16:17]
	v_cmp_lt_i32_e32 vcc, s91, v12
	s_and_saveexec_b64 s[6:7], vcc
	s_xor_b64 s[14:15], exec, s[6:7]
	s_cbranch_execz .LBB0_746
	v_bfe_u32 v9, v12, 6, 4
	v_and_b32_e32 v18, 63, v56
	v_cndmask_b32_e64 v9, v18, v9, s[40:41]
	v_cvt_f32_ubyte0_e32 v9, v9
	v_mul_f32_e32 v9, v7, v9
	v_mul_f32_e32 v9, 0.15915494, v9
	v_sin_f32_e32 v18, v9
	v_cos_f32_e32 v20, v9
	v_pk_mul_f32 v[18:19], v[18:19], v[16:17] op_sel:[0,1] op_sel_hi:[0,0]
	v_pk_mul_f32 v[22:23], v[20:21], v[16:17] op_sel_hi:[0,1]
	v_pk_fma_f32 v[16:17], v[20:21], v[16:17], v[18:19] op_sel_hi:[0,1,1]
	v_sub_f32_e32 v16, v22, v18
	s_andn2_saveexec_b64 s[20:21], s[14:15]
	s_cbranch_execnz .LBB0_747

.LBB0_752:
	s_or_b64 exec, exec, s[14:15]
	v_bfe_u32 v12, v16, 16, 1
	v_add3_u32 v14, v16, v12, s27
	v_lshl_add_u64 v[12:13], v[18:19], 0, v[0:1]
	global_store_short_d16_hi v[12:13], v14, off
	v_bfe_u32 v14, v17, 16, 1
	v_add3_u32 v14, v17, v14, s27
	global_store_short_d16_hi v[12:13], v14, off offset:128
	s_waitcnt vmcnt(14)
	v_lshlrev_b32_e32 v13, 16, v55
	v_lshlrev_b32_e32 v12, 16, v54
	v_pk_mul_f32 v[14:15], v[12:13], v[12:13]
	v_cmp_gt_i32_e32 vcc, 4, v52
	v_add_f32_e32 v14, v14, v15
	v_ashrrev_i32_e32 v9, 31, v8
	v_cmp_lt_i32_e64 s[42:43], 3, v52
	s_waitcnt lgkmcnt(0)
	s_nop 1
	v_add_f32_dpp v15, v14, v14 quad_perm:[1,0,3,2] row_mask:0xf bank_mask:0xf
	s_nop 1
	v_add_f32_dpp v15, v15, v15 quad_perm:[2,3,0,1] row_mask:0xf bank_mask:0xf
	s_nop 1
	v_add_f32_dpp v15, v15, v15 row_ror:4 row_mask:0xf bank_mask:0xf
	s_nop 1
	v_add_f32_dpp v15, v15, v15 row_ror:8 row_mask:0xf bank_mask:0xf
	s_nop 1
	v_readlane_b32 s96, v15, 0
	v_readlane_b32 s97, v15, 16
	v_readlane_b32 s98, v15, 32
	v_readlane_b32 s99, v15, 48
	v_mov_b32_e32 v14, s96
	v_add_f32_e32 v14, s97, v14
	v_add_f32_e32 v14, s98, v14
	v_add_f32_e32 v14, s99, v14
	v_fmamk_f32 v14, v14, 0x3c000000, v203
	v_cmp_gt_f32_e64 s[44:45], s87, v14
	v_mul_f32_e32 v15, 0x4b800000, v14
	s_nop 0
	v_cndmask_b32_e64 v14, v14, v15, s[44:45]
	v_rsq_f32_e32 v14, v14
	s_nop 0
	v_mul_f32_e32 v15, 0x45800000, v14
	v_cndmask_b32_e64 v14, v14, v15, s[44:45]
	v_pk_mul_f32 v[12:13], v[14:15], v[12:13] op_sel_hi:[0,1]
	v_cndmask_b32_e32 v15, v5, v3, vcc
	v_cndmask_b32_e32 v14, v6, v4, vcc
	v_pk_mul_f32 v[12:13], v[14:15], v[12:13]
	v_cmp_lt_i32_e32 vcc, s91, v8
	s_and_saveexec_b64 s[6:7], vcc
	s_xor_b64 s[14:15], exec, s[6:7]
	s_cbranch_execz .LBB0_756
	v_bfe_u32 v14, v8, 6, 4
	v_and_b32_e32 v15, 63, v53
	v_cndmask_b32_e64 v14, v15, v14, s[40:41]
	v_cvt_f32_ubyte0_e32 v14, v14
	v_mul_f32_e32 v14, v7, v14
	v_mul_f32_e32 v15, 0.15915494, v14
	v_sin_f32_e32 v14, v15
	v_cos_f32_e32 v16, v15
	v_pk_mul_f32 v[14:15], v[14:15], v[12:13] op_sel:[0,1] op_sel_hi:[0,0]
	v_pk_mul_f32 v[18:19], v[16:17], v[12:13] op_sel_hi:[0,1]
	v_pk_fma_f32 v[12:13], v[16:17], v[12:13], v[14:15] op_sel_hi:[0,1,1]
	v_sub_f32_e32 v12, v18, v14
	s_andn2_saveexec_b64 s[20:21], s[14:15]
	s_cbranch_execnz .LBB0_757

.LBB0_1041:
	s_or_b64 exec, exec, s[52:53]
	s_waitcnt vmcnt(0)
	v_mov_b32_e32 v116, v91
	v_mov_b32_e32 v117, v95
	v_mov_b32_e32 v114, v90
	v_mov_b32_e32 v115, v94
	v_pk_mul_f32 v[116:117], v[116:117], v[116:117]
	v_mov_b32_e32 v118, v83
	v_pk_fma_f32 v[114:115], v[114:115], v[114:115], v[116:117]
	v_mov_b32_e32 v116, v92
	v_mov_b32_e32 v117, v96
	v_pk_fma_f32 v[114:115], v[116:117], v[116:117], v[114:115]
	v_mov_b32_e32 v116, v93
	v_mov_b32_e32 v117, v97
	v_mov_b32_e32 v119, v87
	v_pk_fma_f32 v[114:115], v[116:117], v[116:117], v[114:115]
	v_mov_b32_e32 v116, v82
	v_mov_b32_e32 v117, v86
	v_pk_mul_f32 v[118:119], v[118:119], v[118:119]
	v_add_f32_e32 v0, v114, v115
	v_pk_fma_f32 v[116:117], v[116:117], v[116:117], v[118:119]
	v_mov_b32_e32 v118, v84
	v_mov_b32_e32 v119, v88
	v_pk_fma_f32 v[116:117], v[118:119], v[118:119], v[116:117]
	v_mov_b32_e32 v118, v85
	v_mov_b32_e32 v119, v89
	v_pk_fma_f32 v[116:117], v[118:119], v[118:119], v[116:117]
	s_nop 0
	v_add_f32_e32 v0, v117, v0
	v_add_f32_e32 v0, v116, v0
	s_waitcnt lgkmcnt(0)
	s_nop 1
	v_add_f32_dpp v114, v0, v0 quad_perm:[1,0,3,2] row_mask:0xf bank_mask:0xf
	s_nop 1
	v_add_f32_dpp v114, v114, v114 quad_perm:[2,3,0,1] row_mask:0xf bank_mask:0xf
	s_nop 1
	v_add_f32_dpp v114, v114, v114 row_ror:4 row_mask:0xf bank_mask:0xf
	s_nop 1
	v_add_f32_dpp v114, v114, v114 row_ror:8 row_mask:0xf bank_mask:0xf
	s_nop 1
	v_readlane_b32 s96, v114, 0
	v_readlane_b32 s97, v114, 16
	v_readlane_b32 s98, v114, 32
	v_readlane_b32 s99, v114, 48
	v_mov_b32_e32 v0, s96
	v_add_f32_e32 v0, s97, v0
	v_add_f32_e32 v0, s98, v0
	v_add_f32_e32 v0, s99, v0
	v_fmamk_f32 v0, v0, 0x3a800000, v203
	v_mul_f32_e32 v114, 0x4b800000, v0
	v_cmp_gt_f32_e32 vcc, s87, v0
	s_nop 1
	v_cndmask_b32_e32 v0, v0, v114, vcc
	v_rsq_f32_e32 v0, v0
	s_nop 0
	v_mul_f32_e32 v114, 0x45800000, v0
	v_cndmask_b32_e32 v178, v0, v114, vcc
	s_and_saveexec_b64 s[52:53], s[40:41]
	s_cbranch_execz .LBB0_1043
	v_mov_b32_e32 v116, v55
	v_mov_b32_e32 v117, v51
	v_mov_b32_e32 v114, v54
	v_mov_b32_e32 v115, v50
	v_pk_mul_f32 v[116:117], v[116:117], v[116:117]
	v_mov_b32_e32 v118, v63
	v_pk_fma_f32 v[114:115], v[114:115], v[114:115], v[116:117]
	v_mov_b32_e32 v116, v56
	v_mov_b32_e32 v117, v52
	v_pk_fma_f32 v[114:115], v[116:117], v[116:117], v[114:115]
	v_mov_b32_e32 v116, v57
	v_mov_b32_e32 v117, v53
	v_mov_b32_e32 v119, v59
	v_pk_fma_f32 v[114:115], v[116:117], v[116:117], v[114:115]
	v_mov_b32_e32 v116, v62
	v_mov_b32_e32 v117, v58
	v_pk_mul_f32 v[118:119], v[118:119], v[118:119]
	v_add_f32_e32 v0, v114, v115
	v_pk_fma_f32 v[116:117], v[116:117], v[116:117], v[118:119]
	v_mov_b32_e32 v118, v64
	v_mov_b32_e32 v119, v60
	v_pk_fma_f32 v[116:117], v[118:119], v[118:119], v[116:117]
	v_mov_b32_e32 v118, v65
	v_mov_b32_e32 v119, v61
	v_pk_fma_f32 v[116:117], v[118:119], v[118:119], v[116:117]
	s_nop 0
	v_add_f32_e32 v0, v117, v0
	v_add_f32_e32 v0, v116, v0
	s_waitcnt lgkmcnt(0)
	s_nop 1
	v_add_f32_dpp v114, v0, v0 quad_perm:[1,0,3,2] row_mask:0xf bank_mask:0xf
	s_nop 1
	v_add_f32_dpp v114, v114, v114 quad_perm:[2,3,0,1] row_mask:0xf bank_mask:0xf
	s_nop 1
	v_add_f32_dpp v114, v114, v114 row_ror:4 row_mask:0xf bank_mask:0xf
	s_nop 1
	v_add_f32_dpp v114, v114, v114 row_ror:8 row_mask:0xf bank_mask:0xf
	s_nop 1
	v_readlane_b32 s96, v114, 0
	v_readlane_b32 s97, v114, 16
	v_readlane_b32 s98, v114, 32
	v_readlane_b32 s99, v114, 48
	v_mov_b32_e32 v0, s96
	v_add_f32_e32 v0, s97, v0
	v_add_f32_e32 v0, s98, v0
	v_add_f32_e32 v0, s99, v0
	v_fmamk_f32 v0, v0, 0x3a800000, v203
	v_mul_f32_e32 v114, 0x4b800000, v0
	v_cmp_gt_f32_e32 vcc, s87, v0
	s_nop 1
	v_cndmask_b32_e32 v0, v0, v114, vcc
	v_rsq_f32_e32 v0, v0
	s_nop 0
	v_mul_f32_e32 v114, 0x45800000, v0
	v_cndmask_b32_e32 v179, v0, v114, vcc
